# P5 up-proj epilogue: 8 ssq loads issued up front, single wait (plus P7 batched loads)
# baseline (speedup 1.0000x reference)
.LBB0_693:
	s_lshl_b32 s15, s22, 8
	s_add_i32 s15, s15, s44
	v_or_b32_e32 v150, s15, v1
	v_ashrrev_i32_e32 v151, 31, v150
	v_lshl_add_u64 v[148:149], v[150:151], 2, s[8:9]
	global_load_dword v138, v[148:149], off
	global_load_dword v180, v[148:149], off offset:64
	global_load_dword v181, v[148:149], off offset:128
	global_load_dword v182, v[148:149], off offset:192
	global_load_dword v183, v[148:149], off offset:512
	global_load_dword v184, v[148:149], off offset:576
	global_load_dword v185, v[148:149], off offset:640
	global_load_dword v186, v[148:149], off offset:704
	s_lshl_b32 s17, s23, 8
	s_or_b32 s17, s17, s45
	s_and_b32 s24, s15, 0xffffff00
	s_ashr_i32 s15, s17, 6
	s_add_i32 s22, s24, s15
	s_ashr_i32 s23, s22, 31
	s_lshl_b64 s[22:23], s[22:23], 15
	s_add_u32 s22, s10, s22
	s_addc_u32 s23, s11, s23
	s_or_b32 s17, s15, 2
	s_add_i32 s24, s17, s24
	v_lshlrev_b32_e32 v151, 6, v150
	s_ashr_i32 s25, s24, 31
	v_or_b32_e32 v170, 16, v150
	v_and_or_b32 v172, v151, s51, v154
	s_lshl_b64 s[24:25], s[24:25], 15
	v_ashrrev_i32_e32 v171, 31, v170
	v_lshlrev_b32_e32 v178, 1, v172
	s_add_u32 s24, s10, s24
	v_lshl_add_u64 v[172:173], v[170:171], 2, s[8:9]
	s_addc_u32 s25, s11, s25
	s_andn2_b64 vcc, exec, s[4:5]
	s_mov_b64 s[4:5], -1
	s_waitcnt vmcnt(0)
	v_fmamk_f32 v138, v138, 0x39800000, v169
	v_rsq_f32_e32 v138, v138
	s_nop 0
	v_pk_mul_f32 v[128:129], v[128:129], v[138:139] op_sel_hi:[1,0]
	v_pk_mul_f32 v[126:127], v[126:127], v[138:139] op_sel_hi:[1,0]
	v_pk_mul_f32 v[124:125], v[124:125], v[138:139] op_sel_hi:[1,0]
	v_pk_mul_f32 v[122:123], v[122:123], v[138:139] op_sel_hi:[1,0]
	v_pk_mul_f32 v[120:121], v[120:121], v[138:139] op_sel_hi:[1,0]
	v_pk_mul_f32 v[118:119], v[118:119], v[138:139] op_sel_hi:[1,0]
	v_pk_mul_f32 v[116:117], v[116:117], v[138:139] op_sel_hi:[1,0]
	v_pk_mul_f32 v[114:115], v[114:115], v[138:139] op_sel_hi:[1,0]
	v_max_f32_e32 v126, 0, v126
	v_max_f32_e32 v122, 0, v122
	v_max_f32_e32 v127, 0, v127
	v_max_f32_e32 v123, 0, v123
	v_max_f32_e32 v128, 0, v128
	v_max_f32_e32 v124, 0, v124
	v_max_f32_e32 v129, 0, v129
	v_max_f32_e32 v125, 0, v125
	v_max_f32_e32 v118, 0, v118
	v_max_f32_e32 v114, 0, v114
	v_max_f32_e32 v119, 0, v119
	v_max_f32_e32 v115, 0, v115
	v_max_f32_e32 v120, 0, v120
	v_max_f32_e32 v116, 0, v116
	v_max_f32_e32 v121, 0, v121
	v_max_f32_e32 v117, 0, v117
	v_pk_mul_f32 v[126:127], v[126:127], v[126:127]
	v_pk_mul_f32 v[122:123], v[122:123], v[122:123]
	v_pk_mul_f32 v[128:129], v[128:129], v[128:129]
	v_pk_mul_f32 v[124:125], v[124:125], v[124:125]
	v_pk_mul_f32 v[118:119], v[118:119], v[118:119]
	v_pk_mul_f32 v[174:175], v[114:115], v[114:115]
	v_pk_mul_f32 v[120:121], v[120:121], v[120:121]
	v_pk_mul_f32 v[176:177], v[116:117], v[116:117]
	v_cvt_pk_bf16_f32 v114, v126, v127
	v_cvt_pk_bf16_f32 v115, v128, v129
	v_cvt_pk_bf16_f32 v116, v122, v123
	v_cvt_pk_bf16_f32 v117, v124, v125
	v_cvt_pk_bf16_f32 v118, v118, v119
	v_cvt_pk_bf16_f32 v119, v120, v121
	v_cvt_pk_bf16_f32 v120, v174, v175
	v_cvt_pk_bf16_f32 v121, v176, v177
	global_store_dwordx4 v178, v[114:117], s[22:23]
	global_store_dwordx4 v178, v[118:121], s[24:25]
	s_nop 0
	v_lshlrev_b32_e32 v117, 6, v170
	v_and_or_b32 v117, v117, s52, v154
	v_or_b32_e32 v114, 32, v150
	v_ashrrev_i32_e32 v115, 31, v114
	v_lshl_add_u64 v[118:119], v[114:115], 2, s[8:9]
	v_lshlrev_b32_e32 v115, 1, v117
	v_fmamk_f32 v116, v180, 0x39800000, v169
	v_rsq_f32_e32 v116, v116
	s_nop 0
	v_pk_mul_f32 v[112:113], v[112:113], v[116:117] op_sel_hi:[1,0]
	v_pk_mul_f32 v[110:111], v[110:111], v[116:117] op_sel_hi:[1,0]
	v_pk_mul_f32 v[108:109], v[108:109], v[116:117] op_sel_hi:[1,0]
	v_pk_mul_f32 v[106:107], v[106:107], v[116:117] op_sel_hi:[1,0]
	v_pk_mul_f32 v[104:105], v[104:105], v[116:117] op_sel_hi:[1,0]
	v_pk_mul_f32 v[102:103], v[102:103], v[116:117] op_sel_hi:[1,0]
	v_pk_mul_f32 v[100:101], v[100:101], v[116:117] op_sel_hi:[1,0]
	v_pk_mul_f32 v[98:99], v[98:99], v[116:117] op_sel_hi:[1,0]
	v_max_f32_e32 v110, 0, v110
	v_max_f32_e32 v106, 0, v106
	v_max_f32_e32 v111, 0, v111
	v_max_f32_e32 v107, 0, v107
	v_max_f32_e32 v112, 0, v112
	v_max_f32_e32 v108, 0, v108
	v_max_f32_e32 v113, 0, v113
	v_max_f32_e32 v109, 0, v109
	v_max_f32_e32 v102, 0, v102
	v_max_f32_e32 v98, 0, v98
	v_max_f32_e32 v103, 0, v103
	v_max_f32_e32 v99, 0, v99
	v_max_f32_e32 v104, 0, v104
	v_max_f32_e32 v100, 0, v100
	v_max_f32_e32 v105, 0, v105
	v_max_f32_e32 v101, 0, v101
	v_pk_mul_f32 v[110:111], v[110:111], v[110:111]
	v_pk_mul_f32 v[106:107], v[106:107], v[106:107]
	v_pk_mul_f32 v[112:113], v[112:113], v[112:113]
	v_pk_mul_f32 v[108:109], v[108:109], v[108:109]
	v_pk_mul_f32 v[102:103], v[102:103], v[102:103]
	v_pk_mul_f32 v[116:117], v[98:99], v[98:99]
	v_pk_mul_f32 v[104:105], v[104:105], v[104:105]
	v_pk_mul_f32 v[120:121], v[100:101], v[100:101]
	v_cvt_pk_bf16_f32 v98, v110, v111
	v_cvt_pk_bf16_f32 v99, v112, v113
	v_cvt_pk_bf16_f32 v100, v106, v107
	v_cvt_pk_bf16_f32 v101, v108, v109
	v_cvt_pk_bf16_f32 v102, v102, v103
	v_cvt_pk_bf16_f32 v103, v104, v105
	v_cvt_pk_bf16_f32 v104, v116, v117
	v_cvt_pk_bf16_f32 v105, v120, v121
	global_store_dwordx4 v115, v[98:101], s[22:23]
	global_store_dwordx4 v115, v[102:105], s[24:25]
	s_nop 0
	v_lshlrev_b32_e32 v101, 6, v114
	v_and_or_b32 v101, v101, s53, v154
	v_or_b32_e32 v98, 48, v150
	v_ashrrev_i32_e32 v99, 31, v98
	v_lshl_add_u64 v[102:103], v[98:99], 2, s[8:9]
	v_lshlrev_b32_e32 v99, 1, v101
	v_fmamk_f32 v100, v181, 0x39800000, v169
	v_rsq_f32_e32 v100, v100
	s_nop 0
	v_pk_mul_f32 v[96:97], v[96:97], v[100:101] op_sel_hi:[1,0]
	v_pk_mul_f32 v[94:95], v[94:95], v[100:101] op_sel_hi:[1,0]
	v_pk_mul_f32 v[92:93], v[92:93], v[100:101] op_sel_hi:[1,0]
	v_pk_mul_f32 v[90:91], v[90:91], v[100:101] op_sel_hi:[1,0]
	v_pk_mul_f32 v[88:89], v[88:89], v[100:101] op_sel_hi:[1,0]
	v_pk_mul_f32 v[86:87], v[86:87], v[100:101] op_sel_hi:[1,0]
	v_pk_mul_f32 v[84:85], v[84:85], v[100:101] op_sel_hi:[1,0]
	v_pk_mul_f32 v[82:83], v[82:83], v[100:101] op_sel_hi:[1,0]
	v_max_f32_e32 v94, 0, v94
	v_max_f32_e32 v90, 0, v90
	v_max_f32_e32 v95, 0, v95
	v_max_f32_e32 v91, 0, v91
	v_max_f32_e32 v96, 0, v96
	v_max_f32_e32 v92, 0, v92
	v_max_f32_e32 v97, 0, v97
	v_max_f32_e32 v93, 0, v93
	v_max_f32_e32 v86, 0, v86
	v_max_f32_e32 v82, 0, v82
	v_max_f32_e32 v87, 0, v87
	v_max_f32_e32 v83, 0, v83
	v_max_f32_e32 v88, 0, v88
	v_max_f32_e32 v84, 0, v84
	v_max_f32_e32 v89, 0, v89
	v_max_f32_e32 v85, 0, v85
	v_pk_mul_f32 v[94:95], v[94:95], v[94:95]
	v_pk_mul_f32 v[90:91], v[90:91], v[90:91]
	v_pk_mul_f32 v[96:97], v[96:97], v[96:97]
	v_pk_mul_f32 v[92:93], v[92:93], v[92:93]
	v_pk_mul_f32 v[86:87], v[86:87], v[86:87]
	v_pk_mul_f32 v[100:101], v[82:83], v[82:83]
	v_pk_mul_f32 v[88:89], v[88:89], v[88:89]
	v_pk_mul_f32 v[104:105], v[84:85], v[84:85]
	v_cvt_pk_bf16_f32 v82, v94, v95
	v_cvt_pk_bf16_f32 v83, v96, v97
	v_cvt_pk_bf16_f32 v84, v90, v91
	v_cvt_pk_bf16_f32 v85, v92, v93
	v_cvt_pk_bf16_f32 v86, v86, v87
	v_cvt_pk_bf16_f32 v87, v88, v89
	v_cvt_pk_bf16_f32 v88, v100, v101
	v_cvt_pk_bf16_f32 v89, v104, v105
	global_store_dwordx4 v99, v[82:85], s[22:23]
	global_store_dwordx4 v99, v[86:89], s[24:25]
	s_nop 0
	v_lshlrev_b32_e32 v83, 6, v98
	v_and_or_b32 v83, v83, s54, v154
	v_lshlrev_b32_e32 v86, 1, v83
	v_fmamk_f32 v82, v182, 0x39800000, v169
	v_rsq_f32_e32 v82, v82
	s_nop 0
	v_pk_mul_f32 v[80:81], v[80:81], v[82:83] op_sel_hi:[1,0]
	v_pk_mul_f32 v[78:79], v[78:79], v[82:83] op_sel_hi:[1,0]
	v_pk_mul_f32 v[76:77], v[76:77], v[82:83] op_sel_hi:[1,0]
	v_pk_mul_f32 v[74:75], v[74:75], v[82:83] op_sel_hi:[1,0]
	v_pk_mul_f32 v[72:73], v[72:73], v[82:83] op_sel_hi:[1,0]
	v_pk_mul_f32 v[70:71], v[70:71], v[82:83] op_sel_hi:[1,0]
	v_pk_mul_f32 v[68:69], v[68:69], v[82:83] op_sel_hi:[1,0]
	v_pk_mul_f32 v[66:67], v[66:67], v[82:83] op_sel_hi:[1,0]
	v_max_f32_e32 v78, 0, v78
	v_max_f32_e32 v74, 0, v74
	v_max_f32_e32 v79, 0, v79
	v_max_f32_e32 v75, 0, v75
	v_max_f32_e32 v80, 0, v80
	v_max_f32_e32 v76, 0, v76
	v_max_f32_e32 v81, 0, v81
	v_max_f32_e32 v77, 0, v77
	v_max_f32_e32 v70, 0, v70
	v_max_f32_e32 v66, 0, v66
	v_max_f32_e32 v71, 0, v71
	v_max_f32_e32 v67, 0, v67
	v_max_f32_e32 v72, 0, v72
	v_max_f32_e32 v68, 0, v68
	v_max_f32_e32 v73, 0, v73
	v_max_f32_e32 v69, 0, v69
	v_pk_mul_f32 v[78:79], v[78:79], v[78:79]
	v_pk_mul_f32 v[74:75], v[74:75], v[74:75]
	v_pk_mul_f32 v[80:81], v[80:81], v[80:81]
	v_pk_mul_f32 v[76:77], v[76:77], v[76:77]
	v_pk_mul_f32 v[70:71], v[70:71], v[70:71]
	v_pk_mul_f32 v[82:83], v[66:67], v[66:67]
	v_pk_mul_f32 v[72:73], v[72:73], v[72:73]
	v_pk_mul_f32 v[84:85], v[68:69], v[68:69]
	v_cvt_pk_bf16_f32 v66, v78, v79
	v_cvt_pk_bf16_f32 v67, v80, v81
	v_cvt_pk_bf16_f32 v68, v74, v75
	v_cvt_pk_bf16_f32 v69, v76, v77
	v_cvt_pk_bf16_f32 v70, v70, v71
	v_cvt_pk_bf16_f32 v71, v72, v73
	v_cvt_pk_bf16_f32 v72, v82, v83
	v_cvt_pk_bf16_f32 v73, v84, v85
	global_store_dwordx4 v86, v[66:69], s[22:23]
	global_store_dwordx4 v86, v[70:73], s[24:25]
	s_nop 0
	v_add_u32_e32 v66, 0x80, v150
	v_and_b32_e32 v68, 0xffffff00, v66
	v_lshlrev_b32_e32 v66, 6, v66
	v_and_or_b32 v69, v66, s51, v154
	v_add_u32_e32 v66, s15, v68
	v_ashrrev_i32_e32 v67, 31, v66
	v_add_u32_e32 v68, s17, v68
	v_lshlrev_b32_e32 v138, 1, v69
	v_lshlrev_b64 v[66:67], 15, v[66:67]
	v_ashrrev_i32_e32 v69, 31, v68
	v_lshl_add_u64 v[66:67], s[10:11], 0, v[66:67]
	v_lshlrev_b64 v[68:69], 15, v[68:69]
	v_lshl_add_u64 v[70:71], v[66:67], 0, v[138:139]
	v_lshl_add_u64 v[68:69], s[10:11], 0, v[68:69]
	v_lshl_add_u64 v[74:75], v[68:69], 0, v[138:139]
	v_fmamk_f32 v72, v183, 0x39800000, v169
	v_rsq_f32_e32 v72, v72
	s_nop 0
	v_pk_mul_f32 v[64:65], v[64:65], v[72:73] op_sel_hi:[1,0]
	v_pk_mul_f32 v[62:63], v[62:63], v[72:73] op_sel_hi:[1,0]
	v_pk_mul_f32 v[60:61], v[60:61], v[72:73] op_sel_hi:[1,0]
	v_pk_mul_f32 v[58:59], v[58:59], v[72:73] op_sel_hi:[1,0]
	v_pk_mul_f32 v[56:57], v[56:57], v[72:73] op_sel_hi:[1,0]
	v_pk_mul_f32 v[54:55], v[54:55], v[72:73] op_sel_hi:[1,0]
	v_pk_mul_f32 v[52:53], v[52:53], v[72:73] op_sel_hi:[1,0]
	v_pk_mul_f32 v[50:51], v[50:51], v[72:73] op_sel_hi:[1,0]
	v_max_f32_e32 v62, 0, v62
	v_max_f32_e32 v58, 0, v58
	v_max_f32_e32 v63, 0, v63
	v_max_f32_e32 v59, 0, v59
	v_max_f32_e32 v64, 0, v64
	v_max_f32_e32 v60, 0, v60
	v_max_f32_e32 v65, 0, v65
	v_max_f32_e32 v61, 0, v61
	v_max_f32_e32 v54, 0, v54
	v_max_f32_e32 v50, 0, v50
	v_max_f32_e32 v55, 0, v55
	v_max_f32_e32 v51, 0, v51
	v_max_f32_e32 v56, 0, v56
	v_max_f32_e32 v52, 0, v52
	v_max_f32_e32 v57, 0, v57
	v_max_f32_e32 v53, 0, v53
	v_pk_mul_f32 v[62:63], v[62:63], v[62:63]
	v_pk_mul_f32 v[58:59], v[58:59], v[58:59]
	v_pk_mul_f32 v[64:65], v[64:65], v[64:65]
	v_pk_mul_f32 v[60:61], v[60:61], v[60:61]
	v_pk_mul_f32 v[54:55], v[54:55], v[54:55]
	v_pk_mul_f32 v[72:73], v[50:51], v[50:51]
	v_pk_mul_f32 v[56:57], v[56:57], v[56:57]
	v_pk_mul_f32 v[76:77], v[52:53], v[52:53]
	v_cvt_pk_bf16_f32 v50, v62, v63
	v_cvt_pk_bf16_f32 v51, v64, v65
	v_cvt_pk_bf16_f32 v52, v58, v59
	v_cvt_pk_bf16_f32 v53, v60, v61
	v_cvt_pk_bf16_f32 v54, v54, v55
	v_cvt_pk_bf16_f32 v55, v56, v57
	v_cvt_pk_bf16_f32 v56, v72, v73
	v_cvt_pk_bf16_f32 v57, v76, v77
	global_store_dwordx4 v[70:71], v[50:53], off
	global_store_dwordx4 v[74:75], v[54:57], off
	s_nop 0
	v_add_u32_e32 v51, 0x2400, v151
	v_and_or_b32 v51, v51, s52, v154
	v_lshlrev_b32_e32 v138, 1, v51
	v_lshl_add_u64 v[52:53], v[66:67], 0, v[138:139]
	v_lshl_add_u64 v[54:55], v[68:69], 0, v[138:139]
	v_fmamk_f32 v50, v184, 0x39800000, v169
	v_rsq_f32_e32 v50, v50
	s_nop 0
	v_pk_mul_f32 v[48:49], v[48:49], v[50:51] op_sel_hi:[1,0]
	v_pk_mul_f32 v[46:47], v[46:47], v[50:51] op_sel_hi:[1,0]
	v_pk_mul_f32 v[44:45], v[44:45], v[50:51] op_sel_hi:[1,0]
	v_pk_mul_f32 v[42:43], v[42:43], v[50:51] op_sel_hi:[1,0]
	v_pk_mul_f32 v[40:41], v[40:41], v[50:51] op_sel_hi:[1,0]
	v_pk_mul_f32 v[38:39], v[38:39], v[50:51] op_sel_hi:[1,0]
	v_pk_mul_f32 v[36:37], v[36:37], v[50:51] op_sel_hi:[1,0]
	v_pk_mul_f32 v[34:35], v[34:35], v[50:51] op_sel_hi:[1,0]
	v_max_f32_e32 v46, 0, v46
	v_max_f32_e32 v42, 0, v42
	v_max_f32_e32 v47, 0, v47
	v_max_f32_e32 v43, 0, v43
	v_max_f32_e32 v48, 0, v48
	v_max_f32_e32 v44, 0, v44
	v_max_f32_e32 v49, 0, v49
	v_max_f32_e32 v45, 0, v45
	v_max_f32_e32 v38, 0, v38
	v_max_f32_e32 v34, 0, v34
	v_max_f32_e32 v39, 0, v39
	v_max_f32_e32 v35, 0, v35
	v_max_f32_e32 v40, 0, v40
	v_max_f32_e32 v36, 0, v36
	v_max_f32_e32 v41, 0, v41
	v_max_f32_e32 v37, 0, v37
	v_pk_mul_f32 v[46:47], v[46:47], v[46:47]
	v_pk_mul_f32 v[42:43], v[42:43], v[42:43]
	v_pk_mul_f32 v[48:49], v[48:49], v[48:49]
	v_pk_mul_f32 v[44:45], v[44:45], v[44:45]
	v_pk_mul_f32 v[38:39], v[38:39], v[38:39]
	v_pk_mul_f32 v[50:51], v[34:35], v[34:35]
	v_pk_mul_f32 v[40:41], v[40:41], v[40:41]
	v_pk_mul_f32 v[56:57], v[36:37], v[36:37]
	v_cvt_pk_bf16_f32 v34, v46, v47
	v_cvt_pk_bf16_f32 v35, v48, v49
	v_cvt_pk_bf16_f32 v36, v42, v43
	v_cvt_pk_bf16_f32 v37, v44, v45
	v_cvt_pk_bf16_f32 v38, v38, v39
	v_cvt_pk_bf16_f32 v39, v40, v41
	v_cvt_pk_bf16_f32 v40, v50, v51
	v_cvt_pk_bf16_f32 v41, v56, v57
	global_store_dwordx4 v[52:53], v[34:37], off
	global_store_dwordx4 v[54:55], v[38:41], off
	s_nop 0
	v_add_u32_e32 v35, 0x2800, v151
	v_and_or_b32 v35, v35, s53, v154
	v_lshlrev_b32_e32 v138, 1, v35
	v_lshl_add_u64 v[36:37], v[66:67], 0, v[138:139]
	v_lshl_add_u64 v[38:39], v[68:69], 0, v[138:139]
	v_fmamk_f32 v34, v185, 0x39800000, v169
	v_rsq_f32_e32 v34, v34
	s_nop 0
	v_pk_mul_f32 v[32:33], v[32:33], v[34:35] op_sel_hi:[1,0]
	v_pk_mul_f32 v[30:31], v[30:31], v[34:35] op_sel_hi:[1,0]
	v_pk_mul_f32 v[28:29], v[28:29], v[34:35] op_sel_hi:[1,0]
	v_pk_mul_f32 v[26:27], v[26:27], v[34:35] op_sel_hi:[1,0]
	v_pk_mul_f32 v[24:25], v[24:25], v[34:35] op_sel_hi:[1,0]
	v_pk_mul_f32 v[22:23], v[22:23], v[34:35] op_sel_hi:[1,0]
	v_pk_mul_f32 v[20:21], v[20:21], v[34:35] op_sel_hi:[1,0]
	v_pk_mul_f32 v[18:19], v[18:19], v[34:35] op_sel_hi:[1,0]
	v_max_f32_e32 v30, 0, v30
	v_max_f32_e32 v26, 0, v26
	v_max_f32_e32 v31, 0, v31
	v_max_f32_e32 v27, 0, v27
	v_max_f32_e32 v32, 0, v32
	v_max_f32_e32 v28, 0, v28
	v_max_f32_e32 v33, 0, v33
	v_max_f32_e32 v29, 0, v29
	v_max_f32_e32 v22, 0, v22
	v_max_f32_e32 v18, 0, v18
	v_max_f32_e32 v23, 0, v23
	v_max_f32_e32 v19, 0, v19
	v_max_f32_e32 v24, 0, v24
	v_max_f32_e32 v20, 0, v20
	v_max_f32_e32 v25, 0, v25
	v_max_f32_e32 v21, 0, v21
	v_pk_mul_f32 v[30:31], v[30:31], v[30:31]
	v_pk_mul_f32 v[26:27], v[26:27], v[26:27]
	v_pk_mul_f32 v[32:33], v[32:33], v[32:33]
	v_pk_mul_f32 v[28:29], v[28:29], v[28:29]
	v_pk_mul_f32 v[22:23], v[22:23], v[22:23]
	v_pk_mul_f32 v[34:35], v[18:19], v[18:19]
	v_pk_mul_f32 v[24:25], v[24:25], v[24:25]
	v_pk_mul_f32 v[40:41], v[20:21], v[20:21]
	v_cvt_pk_bf16_f32 v18, v30, v31
	v_cvt_pk_bf16_f32 v19, v32, v33
	v_cvt_pk_bf16_f32 v20, v26, v27
	v_cvt_pk_bf16_f32 v21, v28, v29
	v_cvt_pk_bf16_f32 v22, v22, v23
	v_cvt_pk_bf16_f32 v23, v24, v25
	v_cvt_pk_bf16_f32 v24, v34, v35
	v_cvt_pk_bf16_f32 v25, v40, v41
	global_store_dwordx4 v[36:37], v[18:21], off
	global_store_dwordx4 v[38:39], v[22:25], off
	s_nop 0
	v_add_u32_e32 v19, 0x2c00, v151
	v_and_or_b32 v19, v19, s54, v154
	v_lshlrev_b32_e32 v138, 1, v19
	v_lshl_add_u64 v[20:21], v[66:67], 0, v[138:139]
	v_lshl_add_u64 v[22:23], v[68:69], 0, v[138:139]
	v_fmamk_f32 v18, v186, 0x39800000, v169
	v_rsq_f32_e32 v18, v18
	s_nop 0
	v_pk_mul_f32 v[16:17], v[16:17], v[18:19] op_sel_hi:[1,0]
	v_pk_mul_f32 v[14:15], v[14:15], v[18:19] op_sel_hi:[1,0]
	v_pk_mul_f32 v[12:13], v[12:13], v[18:19] op_sel_hi:[1,0]
	v_pk_mul_f32 v[10:11], v[10:11], v[18:19] op_sel_hi:[1,0]
	v_pk_mul_f32 v[8:9], v[8:9], v[18:19] op_sel_hi:[1,0]
	v_pk_mul_f32 v[6:7], v[6:7], v[18:19] op_sel_hi:[1,0]
	v_pk_mul_f32 v[4:5], v[4:5], v[18:19] op_sel_hi:[1,0]
	v_pk_mul_f32 v[2:3], v[2:3], v[18:19] op_sel_hi:[1,0]
	v_max_f32_e32 v14, 0, v14
	v_max_f32_e32 v10, 0, v10
	v_max_f32_e32 v15, 0, v15
	v_max_f32_e32 v11, 0, v11
	v_max_f32_e32 v16, 0, v16
	v_max_f32_e32 v12, 0, v12
	v_max_f32_e32 v17, 0, v17
	v_max_f32_e32 v13, 0, v13
	v_max_f32_e32 v6, 0, v6
	v_max_f32_e32 v2, 0, v2
	v_max_f32_e32 v7, 0, v7
	v_max_f32_e32 v3, 0, v3
	v_max_f32_e32 v8, 0, v8
	v_max_f32_e32 v4, 0, v4
	v_max_f32_e32 v9, 0, v9
	v_max_f32_e32 v5, 0, v5
	v_pk_mul_f32 v[14:15], v[14:15], v[14:15]
	v_pk_mul_f32 v[10:11], v[10:11], v[10:11]
	v_pk_mul_f32 v[16:17], v[16:17], v[16:17]
	v_pk_mul_f32 v[12:13], v[12:13], v[12:13]
	v_pk_mul_f32 v[6:7], v[6:7], v[6:7]
	v_pk_mul_f32 v[18:19], v[2:3], v[2:3]
	v_pk_mul_f32 v[8:9], v[8:9], v[8:9]
	v_pk_mul_f32 v[24:25], v[4:5], v[4:5]
	v_cvt_pk_bf16_f32 v2, v14, v15
	v_cvt_pk_bf16_f32 v3, v16, v17
	v_cvt_pk_bf16_f32 v4, v10, v11
	v_cvt_pk_bf16_f32 v5, v12, v13
	v_cvt_pk_bf16_f32 v6, v6, v7
	v_cvt_pk_bf16_f32 v7, v8, v9
	v_cvt_pk_bf16_f32 v8, v18, v19
	v_cvt_pk_bf16_f32 v9, v24, v25
	global_store_dwordx4 v[20:21], v[2:5], off
	global_store_dwordx4 v[22:23], v[6:9], off
	s_cbranch_vccnz .LBB0_682
	s_andn2_b64 vcc, exec, s[6:7]
	s_cbranch_vccnz .LBB0_681
	s_barrier
	s_branch .LBB0_681
